# stack: fewer acquire-invalidates + loader-wave priority 2 in GEMM load segments + down-proj closing barrier moved into the trailing skinny unit
# speedup vs baseline: 1.0146x; 1.0018x over previous
; #define LAS __attribute__((address_space(3)))
; #define PG8_WAIT_V(n) asm volatile("s_waitcnt vmcnt(" #n ")" ::: "memory")
; #define PG8_BAR __builtin_amdgcn_s_barrier()
; #define SK_LOAD(buf, c) do { _Pragma("unroll") for (int nt = 0; nt < 2; ++nt) fb[buf][nt] = *(const bf16x8*)(pb + nt * rs + 32 * (c)); \
;         _Pragma("unroll") for (int mt = 0; mt < NMT; ++mt) fa[buf][mt] = *(const bf16x8*)(pa + mt * rs + 32 * (c)); } while (0)
; #define SK_MMA(buf) do { _Pragma("unroll") for (int mt = 0; mt < NMT; ++mt) _Pragma("unroll") for (int nt = 0; nt < 2; ++nt) \
;         acc[mt][nt] = __builtin_amdgcn_mfma_f32_16x16x32_bf16(fa[buf][mt], fb[buf][nt], acc[mt][nt], 0, 0, 0); } while (0)
; template <class Epi, class Sched, bool ALIGN_EPI = false, bool SP2 = false>
; __device__ __forceinline__ void gemm_phase(PG8_LAS unsigned char* lds, const Gemm g, const Sched& S, const Epi& E) {
;     ...
;     PG8_WAIT_V(0);
;     if constexpr (!ALIGN_EPI) { if (wr == 0) PG8_BAR; }
;     PG8_BAR;
; template <int MT, class Epi>
; DI void skinny_unit(LAS unsigned char* lds, const bf16_t* A, const bf16_t* Wt, int K, int cgi, int k0, int row0, const Epi& E, int tid) {
;     const int lane = tid & 63, wid = tid >> 6, fr = lane & 15, fq = lane >> 4;
;     const int c0 = cgi * 32;
;     constexpr int NMT = 2 * MT;
;     const bf16_t* pa = A + (size_t)(row0 + fr) * K + k0 + wid * 256 + 8 * fq;
;     const bf16_t* pb = Wt + (size_t)(c0 + fr) * K + k0 + wid * 256 + 8 * fq;
;     const size_t rs = (size_t)16 * K;
;     f32x4 acc[NMT][2];
; #pragma unroll
;     for (int i = 0; i < NMT; ++i) { acc[i][0] = (f32x4){0.f, 0.f, 0.f, 0.f}; acc[i][1] = (f32x4){0.f, 0.f, 0.f, 0.f}; }
;     bf16x8 fb[3][2], fa[3][NMT];
;     ...
;     SK_LOAD(0, 0); SK_LOAD(1, 1);
;     SK_LOAD(2, 2); SK_MMA(0);
;     SK_LOAD(0, 3); SK_MMA(1);
;     SK_LOAD(1, 4); SK_MMA(2);
;     SK_LOAD(2, 5); SK_MMA(0);
;     SK_LOAD(0, 6); SK_MMA(1);
;     SK_LOAD(1, 7); SK_MMA(2);
.LBB0_723:
.LBB0_724:
	s_and_b64 s[0:1], s[8:9], s[10:11]
	s_andn2_b64 vcc, exec, s[0:1]
	s_cbranch_vccnz .LBB0_727
	s_waitcnt lgkmcnt(0)
	s_mov_b64 exec, -1
	v_and_b32_e32 v70, 15, v253
	v_bfe_u32 v71, v253, 4, 2
	v_lshrrev_b32_e32 v72, 6, v253
	v_mul_u32_u24_e32 v64, 0x4000, v70
	v_lshl_add_u32 v64, v72, 9, v64
	v_lshl_add_u32 v64, v71, 4, v64
	v_readfirstlane_b32 s1, v72
	v_and_b32_e32 v69, 63, v253
	v_lshlrev_b32_e32 v69, 4, v69
	v_mul_u32_u24_e32 v65, 0x4000, v72
	v_lshl_add_u32 v65, v71, 9, v65
	v_lshl_add_u32 v65, v70, 2, v65
	v_lshrrev_b32_e32 v73, 2, v253
	v_and_b32_e32 v74, 3, v253
	v_lshlrev_b32_e32 v66, 7, v73
	v_lshl_add_u32 v66, v74, 5, v66
	v_add_u32_e32 v67, 0x10000, v66
	v_lshlrev_b32_e32 v68, 13, v73
	v_lshl_add_u32 v68, v74, 5, v68
	s_add_u32 s2, s60, 0x12400000
	s_addc_u32 s3, s61, 0
	s_add_u32 s8, s60, 0x3f00000
	s_addc_u32 s9, s61, 0
	s_lshl_b32 s1, s1, 16
	s_add_u32 s2, s2, s1
	s_addc_u32 s3, s3, 0
	s_mov_b32 s0, s92
.Lsk7b_loop:
	s_and_b32 s15, s0, 3
	s_lshl_b32 s14, s15, 12
	s_lshl_b32 s16, s15, 19
	s_add_u32 s16, s2, s16
	s_addc_u32 s17, s3, 0
	s_lshr_b32 s12, s0, 2
	s_lshl_b32 s10, s12, 19
	s_add_u32 s10, s10, s14
	s_add_u32 s10, s8, s10
	s_addc_u32 s11, s9, 0
	s_lshl_b32 s14, s15, 20
	s_lshl_b32 s12, s12, 7
	s_add_u32 s14, s14, s12
	s_add_u32 s14, s14, 0x13c00000
	s_add_u32 s14, s60, s14
	s_addc_u32 s15, s61, 0
	s_add_u32 s12, s10, 0x40000
	s_addc_u32 s13, s11, 0
	global_load_dwordx4 v[108:111], v64, s[10:11] offset:0 nt
	global_load_dwordx4 v[148:151], v64, s[10:11] offset:64 nt
	global_load_dwordx4 v[112:115], v64, s[12:13] offset:0 nt
	global_load_dwordx4 v[152:155], v64, s[12:13] offset:64 nt
	global_load_dwordx4 v[76:79], v69, s[16:17] offset:0
	global_load_dwordx4 v[80:83], v69, s[16:17] offset:1024
	global_load_dwordx4 v[84:87], v69, s[16:17] offset:2048
	global_load_dwordx4 v[88:91], v69, s[16:17] offset:3072
	s_add_u32 s16, s16, 0x1000
	s_addc_u32 s17, s17, 0
	global_load_dwordx4 v[92:95], v69, s[16:17] offset:0
	global_load_dwordx4 v[96:99], v69, s[16:17] offset:1024
	global_load_dwordx4 v[100:103], v69, s[16:17] offset:2048
	global_load_dwordx4 v[104:107], v69, s[16:17] offset:3072
	s_add_u32 s16, s16, 0x1000
	s_addc_u32 s17, s17, 0
	global_load_dwordx4 v[116:119], v69, s[16:17] offset:0
	global_load_dwordx4 v[120:123], v69, s[16:17] offset:1024
	global_load_dwordx4 v[124:127], v69, s[16:17] offset:2048
	global_load_dwordx4 v[128:131], v69, s[16:17] offset:3072
	s_add_u32 s16, s16, 0x1000
	s_addc_u32 s17, s17, 0
	global_load_dwordx4 v[132:135], v69, s[16:17] offset:0
	global_load_dwordx4 v[136:139], v69, s[16:17] offset:1024
	global_load_dwordx4 v[140:143], v69, s[16:17] offset:2048
	global_load_dwordx4 v[144:147], v69, s[16:17] offset:3072
	s_add_u32 s16, s16, 0x1000
	s_addc_u32 s17, s17, 0
	global_load_dwordx4 v[188:191], v64, s[10:11] offset:128 nt
	global_load_dwordx4 v[228:231], v64, s[10:11] offset:192 nt
	global_load_dwordx4 v[192:195], v64, s[12:13] offset:128 nt
	global_load_dwordx4 v[232:235], v64, s[12:13] offset:192 nt
	global_load_dwordx4 v[156:159], v69, s[16:17] offset:0
	global_load_dwordx4 v[160:163], v69, s[16:17] offset:1024
	global_load_dwordx4 v[164:167], v69, s[16:17] offset:2048
	global_load_dwordx4 v[168:171], v69, s[16:17] offset:3072
	s_add_u32 s16, s16, 0x1000
	s_addc_u32 s17, s17, 0
	global_load_dwordx4 v[172:175], v69, s[16:17] offset:0
	global_load_dwordx4 v[176:179], v69, s[16:17] offset:1024
	global_load_dwordx4 v[180:183], v69, s[16:17] offset:2048
	global_load_dwordx4 v[184:187], v69, s[16:17] offset:3072
	s_add_u32 s16, s16, 0x1000
	s_addc_u32 s17, s17, 0
	global_load_dwordx4 v[196:199], v69, s[16:17] offset:0
	global_load_dwordx4 v[200:203], v69, s[16:17] offset:1024
	global_load_dwordx4 v[204:207], v69, s[16:17] offset:2048
	global_load_dwordx4 v[208:211], v69, s[16:17] offset:3072
	s_add_u32 s16, s16, 0x1000
	s_addc_u32 s17, s17, 0
	global_load_dwordx4 v[212:215], v69, s[16:17] offset:0
	global_load_dwordx4 v[216:219], v69, s[16:17] offset:1024
	global_load_dwordx4 v[220:223], v69, s[16:17] offset:2048
	global_load_dwordx4 v[224:227], v69, s[16:17] offset:3072
	s_add_u32 s16, s16, 0x1000
	s_addc_u32 s17, s17, 0
	s_waitcnt vmcnt(20)
	v_mfma_f32_16x16x32_bf16 v[0:3], v[76:79], v[108:111], 0
	v_mfma_f32_16x16x32_bf16 v[4:7], v[76:79], v[112:115], 0
	v_mfma_f32_16x16x32_bf16 v[8:11], v[80:83], v[108:111], 0
	v_mfma_f32_16x16x32_bf16 v[12:15], v[80:83], v[112:115], 0
	v_mfma_f32_16x16x32_bf16 v[16:19], v[84:87], v[108:111], 0
	v_mfma_f32_16x16x32_bf16 v[20:23], v[84:87], v[112:115], 0
	v_mfma_f32_16x16x32_bf16 v[24:27], v[88:91], v[108:111], 0
	v_mfma_f32_16x16x32_bf16 v[28:31], v[88:91], v[112:115], 0
	v_mfma_f32_16x16x32_bf16 v[32:35], v[92:95], v[108:111], 0
	v_mfma_f32_16x16x32_bf16 v[36:39], v[92:95], v[112:115], 0
	v_mfma_f32_16x16x32_bf16 v[40:43], v[96:99], v[108:111], 0
	v_mfma_f32_16x16x32_bf16 v[44:47], v[96:99], v[112:115], 0
	v_mfma_f32_16x16x32_bf16 v[48:51], v[100:103], v[108:111], 0
	v_mfma_f32_16x16x32_bf16 v[52:55], v[100:103], v[112:115], 0
	v_mfma_f32_16x16x32_bf16 v[56:59], v[104:107], v[108:111], 0
	v_mfma_f32_16x16x32_bf16 v[60:63], v[104:107], v[112:115], 0
	v_mfma_f32_16x16x32_bf16 v[0:3], v[116:119], v[148:151], v[0:3]
	v_mfma_f32_16x16x32_bf16 v[4:7], v[116:119], v[152:155], v[4:7]
	v_mfma_f32_16x16x32_bf16 v[8:11], v[120:123], v[148:151], v[8:11]
	v_mfma_f32_16x16x32_bf16 v[12:15], v[120:123], v[152:155], v[12:15]
	v_mfma_f32_16x16x32_bf16 v[16:19], v[124:127], v[148:151], v[16:19]
	v_mfma_f32_16x16x32_bf16 v[20:23], v[124:127], v[152:155], v[20:23]
	v_mfma_f32_16x16x32_bf16 v[24:27], v[128:131], v[148:151], v[24:27]
; #define SK_LOAD(buf, c) do { _Pragma("unroll") for (int nt = 0; nt < 2; ++nt) fb[buf][nt] = *(const bf16x8*)(pb + nt * rs + 32 * (c)); \
;         _Pragma("unroll") for (int mt = 0; mt < NMT; ++mt) fa[buf][mt] = *(const bf16x8*)(pa + mt * rs + 32 * (c)); } while (0)
; #define SK_MMA(buf) do { _Pragma("unroll") for (int mt = 0; mt < NMT; ++mt) _Pragma("unroll") for (int nt = 0; nt < 2; ++nt) \
;         acc[mt][nt] = __builtin_amdgcn_mfma_f32_16x16x32_bf16(fa[buf][mt], fb[buf][nt], acc[mt][nt], 0, 0, 0); } while (0)
; template <int MT, class Epi>
; DI void skinny_unit(LAS unsigned char* lds, const bf16_t* A, const bf16_t* Wt, int K, int cgi, int k0, int row0, const Epi& E, int tid) {
;     ...
;     SK_LOAD(0, 0); SK_LOAD(1, 1);
;     SK_LOAD(2, 2); SK_MMA(0);
;     SK_LOAD(0, 3); SK_MMA(1);
;     SK_LOAD(1, 4); SK_MMA(2);
;     SK_LOAD(2, 5); SK_MMA(0);
;     SK_LOAD(0, 6); SK_MMA(1);
;     SK_LOAD(1, 7); SK_MMA(2);
;     SK_MMA(0); SK_MMA(1);
	v_mfma_f32_16x16x32_bf16 v[28:31], v[128:131], v[152:155], v[28:31]
	v_mfma_f32_16x16x32_bf16 v[32:35], v[132:135], v[148:151], v[32:35]
	v_mfma_f32_16x16x32_bf16 v[36:39], v[132:135], v[152:155], v[36:39]
	v_mfma_f32_16x16x32_bf16 v[40:43], v[136:139], v[148:151], v[40:43]
	v_mfma_f32_16x16x32_bf16 v[44:47], v[136:139], v[152:155], v[44:47]
	v_mfma_f32_16x16x32_bf16 v[48:51], v[140:143], v[148:151], v[48:51]
	v_mfma_f32_16x16x32_bf16 v[52:55], v[140:143], v[152:155], v[52:55]
	v_mfma_f32_16x16x32_bf16 v[56:59], v[144:147], v[148:151], v[56:59]
	v_mfma_f32_16x16x32_bf16 v[60:63], v[144:147], v[152:155], v[60:63]
	global_load_dwordx4 v[108:111], v64, s[10:11] offset:256 nt
	global_load_dwordx4 v[148:151], v64, s[10:11] offset:320 nt
	global_load_dwordx4 v[112:115], v64, s[12:13] offset:256 nt
	global_load_dwordx4 v[152:155], v64, s[12:13] offset:320 nt
	global_load_dwordx4 v[76:79], v69, s[16:17] offset:0
	global_load_dwordx4 v[80:83], v69, s[16:17] offset:1024
	global_load_dwordx4 v[84:87], v69, s[16:17] offset:2048
	global_load_dwordx4 v[88:91], v69, s[16:17] offset:3072
	s_add_u32 s16, s16, 0x1000
	s_addc_u32 s17, s17, 0
	global_load_dwordx4 v[92:95], v69, s[16:17] offset:0
	global_load_dwordx4 v[96:99], v69, s[16:17] offset:1024
	global_load_dwordx4 v[100:103], v69, s[16:17] offset:2048
	global_load_dwordx4 v[104:107], v69, s[16:17] offset:3072
	s_add_u32 s16, s16, 0x1000
	s_addc_u32 s17, s17, 0
	global_load_dwordx4 v[116:119], v69, s[16:17] offset:0
	global_load_dwordx4 v[120:123], v69, s[16:17] offset:1024
	global_load_dwordx4 v[124:127], v69, s[16:17] offset:2048
	global_load_dwordx4 v[128:131], v69, s[16:17] offset:3072
	s_add_u32 s16, s16, 0x1000
	s_addc_u32 s17, s17, 0
	global_load_dwordx4 v[132:135], v69, s[16:17] offset:0
	global_load_dwordx4 v[136:139], v69, s[16:17] offset:1024
	global_load_dwordx4 v[140:143], v69, s[16:17] offset:2048
	global_load_dwordx4 v[144:147], v69, s[16:17] offset:3072
	s_add_u32 s16, s16, 0x1000
	s_addc_u32 s17, s17, 0
	s_waitcnt vmcnt(20)
	v_mfma_f32_16x16x32_bf16 v[0:3], v[156:159], v[188:191], v[0:3]
	v_mfma_f32_16x16x32_bf16 v[4:7], v[156:159], v[192:195], v[4:7]
	v_mfma_f32_16x16x32_bf16 v[8:11], v[160:163], v[188:191], v[8:11]
	v_mfma_f32_16x16x32_bf16 v[12:15], v[160:163], v[192:195], v[12:15]
	v_mfma_f32_16x16x32_bf16 v[16:19], v[164:167], v[188:191], v[16:19]
	v_mfma_f32_16x16x32_bf16 v[20:23], v[164:167], v[192:195], v[20:23]
	v_mfma_f32_16x16x32_bf16 v[24:27], v[168:171], v[188:191], v[24:27]
	v_mfma_f32_16x16x32_bf16 v[28:31], v[168:171], v[192:195], v[28:31]
	v_mfma_f32_16x16x32_bf16 v[32:35], v[172:175], v[188:191], v[32:35]
	v_mfma_f32_16x16x32_bf16 v[36:39], v[172:175], v[192:195], v[36:39]
	v_mfma_f32_16x16x32_bf16 v[40:43], v[176:179], v[188:191], v[40:43]
	v_mfma_f32_16x16x32_bf16 v[44:47], v[176:179], v[192:195], v[44:47]
	v_mfma_f32_16x16x32_bf16 v[48:51], v[180:183], v[188:191], v[48:51]
	v_mfma_f32_16x16x32_bf16 v[52:55], v[180:183], v[192:195], v[52:55]
	v_mfma_f32_16x16x32_bf16 v[56:59], v[184:187], v[188:191], v[56:59]
	v_mfma_f32_16x16x32_bf16 v[60:63], v[184:187], v[192:195], v[60:63]
	v_mfma_f32_16x16x32_bf16 v[0:3], v[196:199], v[228:231], v[0:3]
	v_mfma_f32_16x16x32_bf16 v[4:7], v[196:199], v[232:235], v[4:7]
	v_mfma_f32_16x16x32_bf16 v[8:11], v[200:203], v[228:231], v[8:11]
	v_mfma_f32_16x16x32_bf16 v[12:15], v[200:203], v[232:235], v[12:15]
	v_mfma_f32_16x16x32_bf16 v[16:19], v[204:207], v[228:231], v[16:19]
	v_mfma_f32_16x16x32_bf16 v[20:23], v[204:207], v[232:235], v[20:23]
	v_mfma_f32_16x16x32_bf16 v[24:27], v[208:211], v[228:231], v[24:27]
	v_mfma_f32_16x16x32_bf16 v[28:31], v[208:211], v[232:235], v[28:31]
	v_mfma_f32_16x16x32_bf16 v[32:35], v[212:215], v[228:231], v[32:35]
	v_mfma_f32_16x16x32_bf16 v[36:39], v[212:215], v[232:235], v[36:39]
	v_mfma_f32_16x16x32_bf16 v[40:43], v[216:219], v[228:231], v[40:43]
	v_mfma_f32_16x16x32_bf16 v[44:47], v[216:219], v[232:235], v[44:47]
	v_mfma_f32_16x16x32_bf16 v[48:51], v[220:223], v[228:231], v[48:51]
	v_mfma_f32_16x16x32_bf16 v[52:55], v[220:223], v[232:235], v[52:55]
	v_mfma_f32_16x16x32_bf16 v[56:59], v[224:227], v[228:231], v[56:59]
	v_mfma_f32_16x16x32_bf16 v[60:63], v[224:227], v[232:235], v[60:63]
	global_load_dwordx4 v[188:191], v64, s[10:11] offset:384 nt
	global_load_dwordx4 v[228:231], v64, s[10:11] offset:448 nt
	global_load_dwordx4 v[192:195], v64, s[12:13] offset:384 nt
	global_load_dwordx4 v[232:235], v64, s[12:13] offset:448 nt
	global_load_dwordx4 v[156:159], v69, s[16:17] offset:0
	global_load_dwordx4 v[160:163], v69, s[16:17] offset:1024
	global_load_dwordx4 v[164:167], v69, s[16:17] offset:2048
	global_load_dwordx4 v[168:171], v69, s[16:17] offset:3072
	s_add_u32 s16, s16, 0x1000
	s_addc_u32 s17, s17, 0
	global_load_dwordx4 v[172:175], v69, s[16:17] offset:0
	global_load_dwordx4 v[176:179], v69, s[16:17] offset:1024
	global_load_dwordx4 v[180:183], v69, s[16:17] offset:2048
	global_load_dwordx4 v[184:187], v69, s[16:17] offset:3072
	s_add_u32 s16, s16, 0x1000
	s_addc_u32 s17, s17, 0
	global_load_dwordx4 v[196:199], v69, s[16:17] offset:0
	global_load_dwordx4 v[200:203], v69, s[16:17] offset:1024
	global_load_dwordx4 v[204:207], v69, s[16:17] offset:2048
	global_load_dwordx4 v[208:211], v69, s[16:17] offset:3072
	s_add_u32 s16, s16, 0x1000
	s_addc_u32 s17, s17, 0
	global_load_dwordx4 v[212:215], v69, s[16:17] offset:0
	global_load_dwordx4 v[216:219], v69, s[16:17] offset:1024
	global_load_dwordx4 v[220:223], v69, s[16:17] offset:2048
	global_load_dwordx4 v[224:227], v69, s[16:17] offset:3072
	s_waitcnt vmcnt(20)
; #define LAS __attribute__((address_space(3)))
; #define SK_LOAD(buf, c) do { _Pragma("unroll") for (int nt = 0; nt < 2; ++nt) fb[buf][nt] = *(const bf16x8*)(pb + nt * rs + 32 * (c)); \
;         _Pragma("unroll") for (int mt = 0; mt < NMT; ++mt) fa[buf][mt] = *(const bf16x8*)(pa + mt * rs + 32 * (c)); } while (0)
; #define SK_MMA(buf) do { _Pragma("unroll") for (int mt = 0; mt < NMT; ++mt) _Pragma("unroll") for (int nt = 0; nt < 2; ++nt) \
;         acc[mt][nt] = __builtin_amdgcn_mfma_f32_16x16x32_bf16(fa[buf][mt], fb[buf][nt], acc[mt][nt], 0, 0, 0); } while (0)
; template <int MT, class Epi>
; DI void skinny_unit(LAS unsigned char* lds, const bf16_t* A, const bf16_t* Wt, int K, int cgi, int k0, int row0, const Epi& E, int tid) {
;     ...
;     SK_LOAD(0, 6); SK_MMA(1);
;     SK_LOAD(1, 7); SK_MMA(2);
;     SK_MMA(0); SK_MMA(1);
;     ...
;     constexpr int NR = 32 * MT;
;     LAS float* red = (LAS float*)lds;
; #pragma unroll
;     for (int mt = 0; mt < NMT; ++mt)
; #pragma unroll
;         for (int nt = 0; nt < 2; ++nt)
; #pragma unroll
;             for (int j = 0; j < 4; ++j) red[(wid * NR + mt * 16 + 4 * fq + j) * 32 + nt * 16 + fr] = acc[mt][nt][j];
	v_mfma_f32_16x16x32_bf16 v[0:3], v[76:79], v[108:111], v[0:3]
	v_mfma_f32_16x16x32_bf16 v[4:7], v[76:79], v[112:115], v[4:7]
	v_mfma_f32_16x16x32_bf16 v[8:11], v[80:83], v[108:111], v[8:11]
	v_mfma_f32_16x16x32_bf16 v[12:15], v[80:83], v[112:115], v[12:15]
	v_mfma_f32_16x16x32_bf16 v[16:19], v[84:87], v[108:111], v[16:19]
	v_mfma_f32_16x16x32_bf16 v[20:23], v[84:87], v[112:115], v[20:23]
	v_mfma_f32_16x16x32_bf16 v[24:27], v[88:91], v[108:111], v[24:27]
	v_mfma_f32_16x16x32_bf16 v[28:31], v[88:91], v[112:115], v[28:31]
	v_mfma_f32_16x16x32_bf16 v[32:35], v[92:95], v[108:111], v[32:35]
	v_mfma_f32_16x16x32_bf16 v[36:39], v[92:95], v[112:115], v[36:39]
	v_mfma_f32_16x16x32_bf16 v[40:43], v[96:99], v[108:111], v[40:43]
	v_mfma_f32_16x16x32_bf16 v[44:47], v[96:99], v[112:115], v[44:47]
	v_mfma_f32_16x16x32_bf16 v[48:51], v[100:103], v[108:111], v[48:51]
	v_mfma_f32_16x16x32_bf16 v[52:55], v[100:103], v[112:115], v[52:55]
	v_mfma_f32_16x16x32_bf16 v[56:59], v[104:107], v[108:111], v[56:59]
	v_mfma_f32_16x16x32_bf16 v[60:63], v[104:107], v[112:115], v[60:63]
	v_mfma_f32_16x16x32_bf16 v[0:3], v[116:119], v[148:151], v[0:3]
	v_mfma_f32_16x16x32_bf16 v[4:7], v[116:119], v[152:155], v[4:7]
	v_mfma_f32_16x16x32_bf16 v[8:11], v[120:123], v[148:151], v[8:11]
	v_mfma_f32_16x16x32_bf16 v[12:15], v[120:123], v[152:155], v[12:15]
	v_mfma_f32_16x16x32_bf16 v[16:19], v[124:127], v[148:151], v[16:19]
	v_mfma_f32_16x16x32_bf16 v[20:23], v[124:127], v[152:155], v[20:23]
	v_mfma_f32_16x16x32_bf16 v[24:27], v[128:131], v[148:151], v[24:27]
	v_mfma_f32_16x16x32_bf16 v[28:31], v[128:131], v[152:155], v[28:31]
	v_mfma_f32_16x16x32_bf16 v[32:35], v[132:135], v[148:151], v[32:35]
	v_mfma_f32_16x16x32_bf16 v[36:39], v[132:135], v[152:155], v[36:39]
	v_mfma_f32_16x16x32_bf16 v[40:43], v[136:139], v[148:151], v[40:43]
	v_mfma_f32_16x16x32_bf16 v[44:47], v[136:139], v[152:155], v[44:47]
	v_mfma_f32_16x16x32_bf16 v[48:51], v[140:143], v[148:151], v[48:51]
	v_mfma_f32_16x16x32_bf16 v[52:55], v[140:143], v[152:155], v[52:55]
	v_mfma_f32_16x16x32_bf16 v[56:59], v[144:147], v[148:151], v[56:59]
	v_mfma_f32_16x16x32_bf16 v[60:63], v[144:147], v[152:155], v[60:63]
	s_waitcnt vmcnt(0)
	v_mfma_f32_16x16x32_bf16 v[0:3], v[156:159], v[188:191], v[0:3]
	v_mfma_f32_16x16x32_bf16 v[4:7], v[156:159], v[192:195], v[4:7]
	v_mfma_f32_16x16x32_bf16 v[8:11], v[160:163], v[188:191], v[8:11]
	v_mfma_f32_16x16x32_bf16 v[12:15], v[160:163], v[192:195], v[12:15]
	v_mfma_f32_16x16x32_bf16 v[16:19], v[164:167], v[188:191], v[16:19]
	v_mfma_f32_16x16x32_bf16 v[20:23], v[164:167], v[192:195], v[20:23]
	v_mfma_f32_16x16x32_bf16 v[24:27], v[168:171], v[188:191], v[24:27]
	v_mfma_f32_16x16x32_bf16 v[28:31], v[168:171], v[192:195], v[28:31]
	v_mfma_f32_16x16x32_bf16 v[32:35], v[172:175], v[188:191], v[32:35]
	v_mfma_f32_16x16x32_bf16 v[36:39], v[172:175], v[192:195], v[36:39]
	v_mfma_f32_16x16x32_bf16 v[40:43], v[176:179], v[188:191], v[40:43]
	v_mfma_f32_16x16x32_bf16 v[44:47], v[176:179], v[192:195], v[44:47]
	v_mfma_f32_16x16x32_bf16 v[48:51], v[180:183], v[188:191], v[48:51]
	v_mfma_f32_16x16x32_bf16 v[52:55], v[180:183], v[192:195], v[52:55]
	v_mfma_f32_16x16x32_bf16 v[56:59], v[184:187], v[188:191], v[56:59]
	v_mfma_f32_16x16x32_bf16 v[60:63], v[184:187], v[192:195], v[60:63]
	v_mfma_f32_16x16x32_bf16 v[0:3], v[196:199], v[228:231], v[0:3]
	v_mfma_f32_16x16x32_bf16 v[4:7], v[196:199], v[232:235], v[4:7]
	v_mfma_f32_16x16x32_bf16 v[8:11], v[200:203], v[228:231], v[8:11]
	v_mfma_f32_16x16x32_bf16 v[12:15], v[200:203], v[232:235], v[12:15]
	v_mfma_f32_16x16x32_bf16 v[16:19], v[204:207], v[228:231], v[16:19]
	v_mfma_f32_16x16x32_bf16 v[20:23], v[204:207], v[232:235], v[20:23]
	v_mfma_f32_16x16x32_bf16 v[24:27], v[208:211], v[228:231], v[24:27]
	v_mfma_f32_16x16x32_bf16 v[28:31], v[208:211], v[232:235], v[28:31]
	v_mfma_f32_16x16x32_bf16 v[32:35], v[212:215], v[228:231], v[32:35]
	v_mfma_f32_16x16x32_bf16 v[36:39], v[212:215], v[232:235], v[36:39]
	v_mfma_f32_16x16x32_bf16 v[40:43], v[216:219], v[228:231], v[40:43]
	v_mfma_f32_16x16x32_bf16 v[44:47], v[216:219], v[232:235], v[44:47]
	v_mfma_f32_16x16x32_bf16 v[48:51], v[220:223], v[228:231], v[48:51]
	v_mfma_f32_16x16x32_bf16 v[52:55], v[220:223], v[232:235], v[52:55]
	v_mfma_f32_16x16x32_bf16 v[56:59], v[224:227], v[228:231], v[56:59]
	v_mfma_f32_16x16x32_bf16 v[60:63], v[224:227], v[232:235], v[60:63]
	v_add_u32_e32 v77, 0x800, v65
	v_add_u32_e32 v78, 0x1000, v65
	v_add_u32_e32 v79, 0x1800, v65
	v_add_u32_e32 v80, 0x2000, v65
	v_add_u32_e32 v81, 0x2800, v65
	v_add_u32_e32 v82, 0x3000, v65
	v_add_u32_e32 v83, 0x3800, v65
	s_nop 7
	s_nop 3
	s_barrier
; #define LAS __attribute__((address_space(3)))
; template <int MT, class Epi>
; DI void skinny_unit(LAS unsigned char* lds, const bf16_t* A, const bf16_t* Wt, int K, int cgi, int k0, int row0, const Epi& E, int tid) {
;     ...
;     LAS float* red = (LAS float*)lds;
; #pragma unroll
;     for (int mt = 0; mt < NMT; ++mt)
; #pragma unroll
;         for (int nt = 0; nt < 2; ++nt)
; #pragma unroll
;             for (int j = 0; j < 4; ++j) red[(wid * NR + mt * 16 + 4 * fq + j) * 32 + nt * 16 + fr] = acc[mt][nt][j];
;     __syncthreads();
;     if (MT == 4) {
;         const int row = tid >> 2, c8 = (tid & 3) * 8;
;         f32x4 sa = {0.f, 0.f, 0.f, 0.f}, sb = {0.f, 0.f, 0.f, 0.f};
; #pragma unroll
;         for (int w = 0; w < 8; ++w) { sa += *(const LAS f32x4*)(red + (w * NR + row) * 32 + c8); sb += *(const LAS f32x4*)(red + (w * NR + row) * 32 + c8 + 4); }
;         E(row0 + row, c0 + c8, sa); E(row0 + row, c0 + c8 + 4, sb);
;     } else if (tid < 8 * NR) {
;         const int row = tid >> 3, c4 = (tid & 7) * 4;
;         f32x4 sa = {0.f, 0.f, 0.f, 0.f};
; #pragma unroll
;         for (int w = 0; w < 8; ++w) sa += *(const LAS f32x4*)(red + (w * NR + row) * 32 + c4);
;         E(row0 + row, c0 + c4, sa);
;     }
;     __syncthreads();
	ds_write2_b32 v65, v0, v4 offset1:16
	ds_write2_b32 v65, v1, v5 offset0:32 offset1:48
	ds_write2_b32 v65, v2, v6 offset0:64 offset1:80
	ds_write2_b32 v65, v3, v7 offset0:96 offset1:112
	ds_write2_b32 v77, v8, v12 offset1:16
	ds_write2_b32 v77, v9, v13 offset0:32 offset1:48
	ds_write2_b32 v77, v10, v14 offset0:64 offset1:80
	ds_write2_b32 v77, v11, v15 offset0:96 offset1:112
	ds_write2_b32 v78, v16, v20 offset1:16
	ds_write2_b32 v78, v17, v21 offset0:32 offset1:48
	ds_write2_b32 v78, v18, v22 offset0:64 offset1:80
	ds_write2_b32 v78, v19, v23 offset0:96 offset1:112
	ds_write2_b32 v79, v24, v28 offset1:16
	ds_write2_b32 v79, v25, v29 offset0:32 offset1:48
	ds_write2_b32 v79, v26, v30 offset0:64 offset1:80
	ds_write2_b32 v79, v27, v31 offset0:96 offset1:112
	ds_write2_b32 v80, v32, v36 offset1:16
	ds_write2_b32 v80, v33, v37 offset0:32 offset1:48
	ds_write2_b32 v80, v34, v38 offset0:64 offset1:80
	ds_write2_b32 v80, v35, v39 offset0:96 offset1:112
	ds_write2_b32 v81, v40, v44 offset1:16
	ds_write2_b32 v81, v41, v45 offset0:32 offset1:48
	ds_write2_b32 v81, v42, v46 offset0:64 offset1:80
	ds_write2_b32 v81, v43, v47 offset0:96 offset1:112
	ds_write2_b32 v82, v48, v52 offset1:16
	ds_write2_b32 v82, v49, v53 offset0:32 offset1:48
	ds_write2_b32 v82, v50, v54 offset0:64 offset1:80
	ds_write2_b32 v82, v51, v55 offset0:96 offset1:112
	ds_write2_b32 v83, v56, v60 offset1:16
	ds_write2_b32 v83, v57, v61 offset0:32 offset1:48
	ds_write2_b32 v83, v58, v62 offset0:64 offset1:80
	ds_write2_b32 v83, v59, v63 offset0:96 offset1:112
	s_waitcnt lgkmcnt(0)
	s_barrier
	ds_read_b128 v[76:79], v66 offset:0
	ds_read_b128 v[80:83], v66 offset:16
	ds_read_b128 v[84:87], v66 offset:16384
	ds_read_b128 v[88:91], v66 offset:16400
	ds_read_b128 v[92:95], v66 offset:32768
	ds_read_b128 v[96:99], v66 offset:32784
	ds_read_b128 v[100:103], v66 offset:49152
	ds_read_b128 v[104:107], v66 offset:49168
	ds_read_b128 v[108:111], v67 offset:0
	ds_read_b128 v[112:115], v67 offset:16
	ds_read_b128 v[116:119], v67 offset:16384
	ds_read_b128 v[120:123], v67 offset:16400
	ds_read_b128 v[124:127], v67 offset:32768
	ds_read_b128 v[128:131], v67 offset:32784
	ds_read_b128 v[132:135], v67 offset:49152
	ds_read_b128 v[136:139], v67 offset:49168
	s_waitcnt lgkmcnt(12)
	v_pk_add_f32 v[76:77], v[76:77], v[84:85]
	v_pk_add_f32 v[78:79], v[78:79], v[86:87]
	v_pk_add_f32 v[80:81], v[80:81], v[88:89]
	v_pk_add_f32 v[82:83], v[82:83], v[90:91]
	s_waitcnt lgkmcnt(10)
	v_pk_add_f32 v[76:77], v[76:77], v[92:93]
	v_pk_add_f32 v[78:79], v[78:79], v[94:95]
	v_pk_add_f32 v[80:81], v[80:81], v[96:97]
	v_pk_add_f32 v[82:83], v[82:83], v[98:99]
	s_waitcnt lgkmcnt(8)
	v_pk_add_f32 v[76:77], v[76:77], v[100:101]
	v_pk_add_f32 v[78:79], v[78:79], v[102:103]
	v_pk_add_f32 v[80:81], v[80:81], v[104:105]
	v_pk_add_f32 v[82:83], v[82:83], v[106:107]
	s_waitcnt lgkmcnt(6)
	v_pk_add_f32 v[76:77], v[76:77], v[108:109]
	v_pk_add_f32 v[78:79], v[78:79], v[110:111]
	v_pk_add_f32 v[80:81], v[80:81], v[112:113]
	v_pk_add_f32 v[82:83], v[82:83], v[114:115]
	s_waitcnt lgkmcnt(4)
	v_pk_add_f32 v[76:77], v[76:77], v[116:117]
	v_pk_add_f32 v[78:79], v[78:79], v[118:119]
	v_pk_add_f32 v[80:81], v[80:81], v[120:121]
	v_pk_add_f32 v[82:83], v[82:83], v[122:123]
	s_waitcnt lgkmcnt(2)
	v_pk_add_f32 v[76:77], v[76:77], v[124:125]
	v_pk_add_f32 v[78:79], v[78:79], v[126:127]
	v_pk_add_f32 v[80:81], v[80:81], v[128:129]
	v_pk_add_f32 v[82:83], v[82:83], v[130:131]
	s_waitcnt lgkmcnt(0)
	v_pk_add_f32 v[76:77], v[76:77], v[132:133]
	v_pk_add_f32 v[78:79], v[78:79], v[134:135]
	v_pk_add_f32 v[80:81], v[80:81], v[136:137]
	v_pk_add_f32 v[82:83], v[82:83], v[138:139]
	global_store_dwordx4 v68, v[76:79], s[14:15]
	global_store_dwordx4 v68, v[80:83], s[14:15] offset:16
	s_add_i32 s0, s0, s64
	s_cmpk_lt_i32 s0, 0x100
	s_barrier
	s_cbranch_scc1 .Lsk7b_loop
